# speedup vs baseline: 1.0191x; 1.0014x over previous
.LBB0_624:
	s_and_b32 s16, s14, 0x10000
	s_xor_b32 s17, s16, 0x10000
	v_xor_b32_e32 v217, s16, v215
	v_bitop3_b32 v218, v215, s16, 64 bitop3:0x96
	v_bitop3_b32 v220, v216, s16, 64 bitop3:0x96
	v_xor_b32_e32 v219, s17, v216
	v_xor_b32_e32 v221, s17, v215
	s_waitcnt lgkmcnt(2)
	v_mfma_f32_16x16x32_bf16 v[100:103], v[148:151], v[132:135], v[100:103]
	s_add_i32 s15, s14, 0x10000
	s_and_b32 s17, s15, 0x10000
	s_add_i32 s17, s0, s17
	s_lshl_b64 s[98:99], s[10:11], 4
	s_add_u32 s98, s98, s12
	s_addc_u32 s99, s99, s13
	v_lshl_add_u64 v[246:247], v[174:175], 0, s[12:13]
	s_add_i32 m0, s17, 0x800
	v_mfma_f32_16x16x32_bf16 v[104:107], v[148:151], v[136:139], v[104:107]
	global_load_lds_dwordx4 v[246:247], off
	s_add_i32 m0, s17, 0x4800
	v_lshl_add_u64 v[248:249], v[174:175], 0, s[98:99]
	v_mfma_f32_16x16x32_bf16 v[116:119], v[148:151], v[140:143], v[116:119]
	global_load_lds_dwordx4 v[248:249], off
	s_add_i32 m0, s17, 0x8800
	v_lshl_add_u64 v[246:247], v[176:177], 0, s[12:13]
	v_mfma_f32_16x16x32_bf16 v[120:123], v[148:151], v[144:147], v[120:123]
	global_load_lds_dwordx4 v[246:247], off
	s_add_i32 m0, s17, 0xc800
	v_lshl_add_u64 v[248:249], v[176:177], 0, s[98:99]
	ds_read_b128 v[148:151], v217 offset:8192
	v_mfma_f32_16x16x32_bf16 v[108:111], v[152:155], v[132:135], v[108:111]
	ds_read_b128 v[222:225], v220
	global_load_lds_dwordx4 v[248:249], off
	s_add_i32 m0, s17, 0xc00
	v_lshl_add_u64 v[246:247], v[172:173], 0, s[12:13]
	v_mfma_f32_16x16x32_bf16 v[112:115], v[152:155], v[136:139], v[112:115]
	global_load_lds_dwordx4 v[246:247], off
	s_add_i32 m0, s17, 0x4c00
	v_lshl_add_u64 v[248:249], v[172:173], 0, s[98:99]
	v_mfma_f32_16x16x32_bf16 v[124:127], v[152:155], v[140:143], v[124:127]
	global_load_lds_dwordx4 v[248:249], off
	s_add_i32 m0, s17, 0x8c00
	v_lshl_add_u64 v[246:247], v[170:171], 0, s[12:13]
	v_mfma_f32_16x16x32_bf16 v[128:131], v[152:155], v[144:147], v[128:131]
	global_load_lds_dwordx4 v[246:247], off
	s_add_i32 m0, s17, 0xcc00
	v_lshl_add_u64 v[248:249], v[170:171], 0, s[98:99]
	ds_read_b128 v[152:155], v217 offset:10240
	s_waitcnt lgkmcnt(3)
	v_mfma_f32_16x16x32_bf16 v[84:87], v[238:241], v[132:135], v[84:87]
	ds_read_b128 v[226:229], v220 offset:2048
	global_load_lds_dwordx4 v[248:249], off
	v_mfma_f32_16x16x32_bf16 v[88:91], v[238:241], v[136:139], v[88:91]
	v_mfma_f32_16x16x32_bf16 v[68:71], v[238:241], v[140:143], v[68:71]
	v_mfma_f32_16x16x32_bf16 v[72:75], v[238:241], v[144:147], v[72:75]
	ds_read_b128 v[238:241], v217 offset:12288
	v_mfma_f32_16x16x32_bf16 v[92:95], v[242:245], v[132:135], v[92:95]
	ds_read_b128 v[230:233], v220 offset:4096
	v_mfma_f32_16x16x32_bf16 v[96:99], v[242:245], v[136:139], v[96:99]
	v_mfma_f32_16x16x32_bf16 v[76:79], v[242:245], v[140:143], v[76:79]
	v_mfma_f32_16x16x32_bf16 v[80:83], v[242:245], v[144:147], v[80:83]
	ds_read_b128 v[242:245], v217 offset:14336
	s_waitcnt lgkmcnt(4)
	v_mfma_f32_16x16x32_bf16 v[52:55], v[148:151], v[132:135], v[52:55]
	ds_read_b128 v[234:237], v220 offset:6144
	v_mfma_f32_16x16x32_bf16 v[56:59], v[148:151], v[136:139], v[56:59]
	v_mfma_f32_16x16x32_bf16 v[36:39], v[148:151], v[140:143], v[36:39]
	v_mfma_f32_16x16x32_bf16 v[40:43], v[148:151], v[144:147], v[40:43]
	ds_read_b128 v[148:151], v218
	v_mfma_f32_16x16x32_bf16 v[60:63], v[152:155], v[132:135], v[60:63]
	v_mfma_f32_16x16x32_bf16 v[64:67], v[152:155], v[136:139], v[64:67]
	v_mfma_f32_16x16x32_bf16 v[44:47], v[152:155], v[140:143], v[44:47]
	v_mfma_f32_16x16x32_bf16 v[48:51], v[152:155], v[144:147], v[48:51]
	ds_read_b128 v[152:155], v218 offset:2048
	s_waitcnt lgkmcnt(3)
	v_mfma_f32_16x16x32_bf16 v[20:23], v[238:241], v[132:135], v[20:23]
	v_mfma_f32_16x16x32_bf16 v[24:27], v[238:241], v[136:139], v[24:27]
	v_mfma_f32_16x16x32_bf16 v[4:7], v[238:241], v[140:143], v[4:7]
	v_mfma_f32_16x16x32_bf16 v[8:11], v[238:241], v[144:147], v[8:11]
	ds_read_b128 v[238:241], v218 offset:4096
	v_mfma_f32_16x16x32_bf16 v[28:31], v[242:245], v[132:135], v[28:31]
	v_mfma_f32_16x16x32_bf16 v[32:35], v[242:245], v[136:139], v[32:35]
	v_mfma_f32_16x16x32_bf16 v[12:15], v[242:245], v[140:143], v[12:15]
	v_mfma_f32_16x16x32_bf16 v[16:19], v[242:245], v[144:147], v[16:19]
	ds_read_b128 v[242:245], v218 offset:6144
	s_waitcnt lgkmcnt(2)
	v_mfma_f32_16x16x32_bf16 v[100:103], v[148:151], v[222:225], v[100:103]
	v_mfma_f32_16x16x32_bf16 v[104:107], v[148:151], v[226:229], v[104:107]
	v_mfma_f32_16x16x32_bf16 v[116:119], v[148:151], v[230:233], v[116:119]
	v_mfma_f32_16x16x32_bf16 v[120:123], v[148:151], v[234:237], v[120:123]
	ds_read_b128 v[148:151], v218 offset:8192
	v_mfma_f32_16x16x32_bf16 v[108:111], v[152:155], v[222:225], v[108:111]
	v_mfma_f32_16x16x32_bf16 v[112:115], v[152:155], v[226:229], v[112:115]
	v_mfma_f32_16x16x32_bf16 v[124:127], v[152:155], v[230:233], v[124:127]
	v_mfma_f32_16x16x32_bf16 v[128:131], v[152:155], v[234:237], v[128:131]
	ds_read_b128 v[152:155], v218 offset:10240
	s_waitcnt lgkmcnt(2)
	v_mfma_f32_16x16x32_bf16 v[84:87], v[238:241], v[222:225], v[84:87]
	v_mfma_f32_16x16x32_bf16 v[88:91], v[238:241], v[226:229], v[88:91]
	v_mfma_f32_16x16x32_bf16 v[68:71], v[238:241], v[230:233], v[68:71]
	v_mfma_f32_16x16x32_bf16 v[72:75], v[238:241], v[234:237], v[72:75]
	ds_read_b128 v[238:241], v218 offset:12288
	v_mfma_f32_16x16x32_bf16 v[92:95], v[242:245], v[222:225], v[92:95]
	v_mfma_f32_16x16x32_bf16 v[96:99], v[242:245], v[226:229], v[96:99]
	v_mfma_f32_16x16x32_bf16 v[76:79], v[242:245], v[230:233], v[76:79]
	v_mfma_f32_16x16x32_bf16 v[80:83], v[242:245], v[234:237], v[80:83]
	ds_read_b128 v[242:245], v218 offset:14336
	s_waitcnt lgkmcnt(2)
	v_mfma_f32_16x16x32_bf16 v[52:55], v[148:151], v[222:225], v[52:55]
	v_mfma_f32_16x16x32_bf16 v[56:59], v[148:151], v[226:229], v[56:59]
	v_mfma_f32_16x16x32_bf16 v[36:39], v[148:151], v[230:233], v[36:39]
	v_mfma_f32_16x16x32_bf16 v[40:43], v[148:151], v[234:237], v[40:43]
	s_add_i32 s3, s3, 1
	s_min_i32 s38, s3, s1
	s_ashr_i32 s39, s38, 31
	s_lshl_b64 s[38:39], s[38:39], 7
	s_add_i32 s14, s0, s16
	s_add_u32 s16, s38, s10
	s_addc_u32 s17, s39, s11
	s_lshl_b64 s[98:99], s[10:11], 4
	s_add_u32 s98, s98, s38
	s_addc_u32 s99, s99, s39
	v_lshl_add_u64 v[246:247], v[162:163], 0, s[38:39]
	s_mov_b32 m0, s14
	s_waitcnt vmcnt(0) lgkmcnt(0)
	s_barrier
	ds_read_b128 v[132:135], v219
	ds_read_b128 v[136:139], v219 offset:2048
	v_mfma_f32_16x16x32_bf16 v[60:63], v[152:155], v[222:225], v[60:63]
	global_load_lds_dwordx4 v[246:247], off
	s_add_i32 m0, s14, 0x4000
	v_lshl_add_u64 v[248:249], v[162:163], 0, s[98:99]
	ds_read_b128 v[140:143], v219 offset:4096
	ds_read_b128 v[144:147], v219 offset:6144
	v_mfma_f32_16x16x32_bf16 v[64:67], v[152:155], v[226:229], v[64:67]
	global_load_lds_dwordx4 v[248:249], off
	s_add_i32 m0, s14, 0x8000
	v_lshl_add_u64 v[246:247], v[164:165], 0, s[38:39]
	ds_read_b128 v[148:151], v221
	v_mfma_f32_16x16x32_bf16 v[44:47], v[152:155], v[230:233], v[44:47]
	global_load_lds_dwordx4 v[246:247], off
	s_add_i32 m0, s14, 0xc000
	v_lshl_add_u64 v[248:249], v[164:165], 0, s[98:99]
	v_mfma_f32_16x16x32_bf16 v[48:51], v[152:155], v[234:237], v[48:51]
	global_load_lds_dwordx4 v[248:249], off
	s_add_i32 m0, s14, 0x400
	v_lshl_add_u64 v[246:247], v[166:167], 0, s[16:17]
	ds_read_b128 v[152:155], v221 offset:2048
	v_mfma_f32_16x16x32_bf16 v[20:23], v[238:241], v[222:225], v[20:23]
	global_load_lds_dwordx4 v[246:247], off
	s_add_i32 m0, s14, 0x8400
	v_lshl_add_u64 v[248:249], v[168:169], 0, s[16:17]
	v_mfma_f32_16x16x32_bf16 v[24:27], v[238:241], v[226:229], v[24:27]
	global_load_lds_dwordx4 v[248:249], off
	s_add_u32 s98, s98, s10
	s_addc_u32 s99, s99, s11
	v_lshl_add_u64 v[246:247], v[166:167], 0, s[98:99]
	s_add_i32 m0, s14, 0x4400
	v_mfma_f32_16x16x32_bf16 v[4:7], v[238:241], v[230:233], v[4:7]
	global_load_lds_dwordx4 v[246:247], off
	s_add_i32 m0, s14, 0xc400
	v_lshl_add_u64 v[248:249], v[168:169], 0, s[98:99]
	v_mfma_f32_16x16x32_bf16 v[8:11], v[238:241], v[234:237], v[8:11]
	global_load_lds_dwordx4 v[248:249], off
	ds_read_b128 v[238:241], v221 offset:4096
	v_mfma_f32_16x16x32_bf16 v[28:31], v[242:245], v[222:225], v[28:31]
	v_mfma_f32_16x16x32_bf16 v[32:35], v[242:245], v[226:229], v[32:35]
	v_mfma_f32_16x16x32_bf16 v[12:15], v[242:245], v[230:233], v[12:15]
	v_mfma_f32_16x16x32_bf16 v[16:19], v[242:245], v[234:237], v[16:19]
	ds_read_b128 v[242:245], v221 offset:6144
	s_add_u32 s12, s12, 0x80
	s_addc_u32 s13, s13, 0
	s_cmp_eq_u32 s5, s3
	s_mov_b32 s14, s15
	s_cbranch_scc0 .LBB0_624
	s_branch .LBB0_626
